# adds: phase-0 rmsnorm and attention finalize: loop-invariant gain loads (norm gain, subln gain) hoisted; per-store vmcnt(0) waits removed
# speedup vs baseline: 1.0453x; 1.0045x over previous
; #define LAS __attribute__((address_space(3)))
; __device__ __forceinline__ int lane_op() { unsigned z = 0u; asm volatile("" : "+v"(z)); return (int)__builtin_amdgcn_mbcnt_hi(~0u, __builtin_amdgcn_mbcnt_lo(~0u, z)); }
; __device__ __forceinline__ float swap_add(float v) { auto rr = __builtin_amdgcn_permlane32_swap(__float_as_uint(v), __float_as_uint(v), false, false); return __uint_as_float(rr[0]) + __uint_as_float(rr[1]); }
; template <bool STORE> __device__ __forceinline__ void attn_unit(LAS unsigned char* lds, bf16_t* Q, const bf16_t* Kg, const bf16_t* VT, const float* subg, float lam, float outscale, int unit, const int wave_s) {
;     ...
;     const float inv = 1.0f / swap_add(lsum);
;     LAS float* xb = (LAS float*)lds + (wid & 3) * 4096;
;     if (map == 1) {
; #pragma unroll
;         for (int d = 0; d < 4; ++d)
; #pragma unroll
;             for (int r = 0; r < 16; ++r) xb[(d * 16 + r) * 64 + lane] = o[d][r] * inv;
;     }
;     __syncthreads();
;     if (STORE && map == 0) {
;         float ss = 0.f;
; #pragma unroll
;         for (int d = 0; d < 4; ++d)
; #pragma unroll
;             for (int r = 0; r < 16; ++r) { const float v = o[d][r] * inv - lam * xb[(d * 16 + r) * 64 + lane]; o[d][r] = v; ss += v * v; }
;         ss = swap_add(ss);
;         const float rstd = outscale / sqrtf(ss * (1.f / 128.f) + EPS);
;         const int l2 = lane_op();
;         const int hi2 = l2 >> 5;
;         bf16_t* orow = Q + (size_t)(b * SEQ + qrow0 + (l2 & 31)) * DM + h * 128 + 8 * hi2;
; #pragma unroll
;         for (int d = 0; d < 4; ++d)
; #pragma unroll
;             for (int i = 0; i < 4; i += 2) {
;                 const f32x4 ga = *(const f32x4*)(subg + 32 * d + 8 * i + 4 * hi2), gb = *(const f32x4*)(subg + 32 * d + 8 * (i + 1) + 4 * hi2);
.LBB0_668:
	s_andn2_b64 vcc, exec, s[66:67]
	s_waitcnt lgkmcnt(0)
	s_barrier
	s_cbranch_vccnz .LBB0_574
	ds_read2st64_b32 v[92:93], v2 offset1:1
	ds_read2st64_b32 v[98:99], v2 offset0:2 offset1:3
	ds_read2st64_b32 v[126:127], v2 offset0:4 offset1:5
	ds_read2st64_b32 v[128:129], v2 offset0:6 offset1:7
	ds_read2st64_b32 v[130:131], v2 offset0:8 offset1:9
	ds_read2st64_b32 v[132:133], v2 offset0:10 offset1:11
	ds_read2st64_b32 v[134:135], v2 offset0:12 offset1:13
	ds_read2st64_b32 v[136:137], v2 offset0:14 offset1:15
	ds_read2st64_b32 v[104:105], v2 offset0:16 offset1:17
	ds_read2st64_b32 v[102:103], v2 offset0:18 offset1:19
	ds_read2st64_b32 v[138:139], v2 offset0:20 offset1:21
	ds_read2st64_b32 v[140:141], v2 offset0:22 offset1:23
	ds_read2st64_b32 v[118:119], v2 offset0:24 offset1:25
	ds_read2st64_b32 v[120:121], v2 offset0:26 offset1:27
	ds_read2st64_b32 v[122:123], v2 offset0:28 offset1:29
	ds_read2st64_b32 v[124:125], v2 offset0:30 offset1:31
	ds_read2st64_b32 v[110:111], v2 offset0:32 offset1:33
	ds_read2st64_b32 v[112:113], v2 offset0:34 offset1:35
	ds_read2st64_b32 v[114:115], v2 offset0:36 offset1:37
	ds_read2st64_b32 v[116:117], v2 offset0:38 offset1:39
	ds_read2st64_b32 v[96:97], v2 offset0:40 offset1:41
	ds_read2st64_b32 v[100:101], v2 offset0:42 offset1:43
	ds_read2st64_b32 v[106:107], v2 offset0:44 offset1:45
	ds_read2st64_b32 v[108:109], v2 offset0:46 offset1:47
	ds_read2st64_b32 v[86:87], v2 offset0:48 offset1:49
	ds_read2st64_b32 v[88:89], v2 offset0:50 offset1:51
	ds_read2st64_b32 v[90:91], v2 offset0:52 offset1:53
	ds_read2st64_b32 v[94:95], v2 offset0:54 offset1:55
	ds_read2st64_b32 v[80:81], v2 offset0:56 offset1:57
	ds_read2st64_b32 v[82:83], v2 offset0:58 offset1:59
	ds_read2st64_b32 v[84:85], v2 offset0:60 offset1:61
	ds_read2st64_b32 v[2:3], v2 offset0:62 offset1:63
	s_lshl_b32 s16, s63, 1
	s_mov_b32 s12, 0xf800000
	s_waitcnt lgkmcnt(0)
	v_pk_mul_f32 v[2:3], s[14:15], v[2:3]
	s_nop 0
	v_pk_fma_f32 v[12:13], v[30:31], v[0:1], v[2:3] op_sel_hi:[1,0,1] neg_lo:[0,0,1] neg_hi:[0,0,1]
	v_pk_mul_f32 v[30:31], s[14:15], v[128:129]
	v_mov_b32_e32 v2, v1
	v_pk_fma_f32 v[70:71], v[70:71], v[0:1], v[30:31] op_sel_hi:[1,0,1] neg_lo:[0,0,1] neg_hi:[0,0,1]
	v_pk_mul_f32 v[30:31], s[14:15], v[126:127]
	s_nop 0
	v_pk_fma_f32 v[68:69], v[68:69], v[0:1], v[30:31] op_sel_hi:[1,0,1] neg_lo:[0,0,1] neg_hi:[0,0,1]
	v_pk_mul_f32 v[30:31], s[14:15], v[98:99]
	v_mbcnt_lo_u32_b32 v2, -1, v2
	v_pk_fma_f32 v[66:67], v[66:67], v[0:1], v[30:31] op_sel_hi:[1,0,1] neg_lo:[0,0,1] neg_hi:[0,0,1]
	v_pk_mul_f32 v[30:31], s[14:15], v[92:93]
	v_mbcnt_hi_u32_b32 v2, -1, v2
	v_pk_fma_f32 v[92:93], v[64:65], v[0:1], v[30:31] op_sel_hi:[1,0,1] neg_lo:[0,0,1] neg_hi:[0,0,1]
	v_mul_f32_e32 v64, v67, v67
	v_mul_f32_e32 v30, v93, v93
	v_pk_fma_f32 v[30:31], v[92:93], v[92:93], v[30:31] op_sel_hi:[1,1,0]
	v_ashrrev_i32_e32 v6, 5, v2
	v_pk_fma_f32 v[30:31], v[66:67], v[66:67], v[30:31]
	v_and_or_b32 v2, v2, 31, s62
	v_pk_add_f32 v[30:31], v[30:31], v[64:65] op_sel_hi:[1,0]
	v_mul_f32_e32 v64, v69, v69
	v_pk_fma_f32 v[30:31], v[68:69], v[68:69], v[30:31]
	v_ashrrev_i32_e32 v3, 31, v2
	v_pk_add_f32 v[30:31], v[30:31], v[64:65] op_sel_hi:[1,0]
	v_mul_f32_e32 v64, v71, v71
	v_pk_fma_f32 v[30:31], v[70:71], v[70:71], v[30:31]
	v_lshlrev_b64 v[2:3], 11, v[2:3]
	v_pk_add_f32 v[30:31], v[30:31], v[64:65] op_sel_hi:[1,0]
	v_pk_mul_f32 v[64:65], s[14:15], v[136:137]
	v_lshl_add_u64 v[2:3], s[48:49], 0, v[2:3]
	v_pk_fma_f32 v[64:65], v[78:79], v[0:1], v[64:65] op_sel_hi:[1,0,1] neg_lo:[0,0,1] neg_hi:[0,0,1]
	v_pk_mul_f32 v[78:79], s[14:15], v[134:135]
	v_lshlrev_b32_e32 v4, 3, v6
	v_pk_fma_f32 v[76:77], v[76:77], v[0:1], v[78:79] op_sel_hi:[1,0,1] neg_lo:[0,0,1] neg_hi:[0,0,1]
	v_pk_mul_f32 v[78:79], s[14:15], v[132:133]
	v_lshl_add_u64 v[2:3], v[2:3], 0, s[16:17]
	v_pk_fma_f32 v[74:75], v[74:75], v[0:1], v[78:79] op_sel_hi:[1,0,1] neg_lo:[0,0,1] neg_hi:[0,0,1]
	v_pk_mul_f32 v[78:79], s[14:15], v[130:131]
	v_ashrrev_i32_e32 v5, 31, v4
	v_pk_fma_f32 v[98:99], v[72:73], v[0:1], v[78:79] op_sel_hi:[1,0,1] neg_lo:[0,0,1] neg_hi:[0,0,1]
	v_lshl_add_u64 v[10:11], v[4:5], 1, v[2:3]
	v_pk_fma_f32 v[30:31], v[98:99], v[98:99], v[30:31]
	v_mul_f32_e32 v72, v99, v99
	v_pk_add_f32 v[30:31], v[30:31], v[72:73] op_sel_hi:[1,0]
	v_mul_f32_e32 v72, v75, v75
	v_pk_fma_f32 v[30:31], v[74:75], v[74:75], v[30:31]
	v_lshlrev_b32_e32 v2, 2, v6
	v_pk_add_f32 v[30:31], v[30:31], v[72:73] op_sel_hi:[1,0]
	v_mul_f32_e32 v72, v77, v77
	v_pk_fma_f32 v[30:31], v[76:77], v[76:77], v[30:31]
	v_ashrrev_i32_e32 v3, 31, v2
	v_pk_add_f32 v[30:31], v[30:31], v[72:73] op_sel_hi:[1,0]
	v_mul_f32_e32 v72, v65, v65
	v_pk_fma_f32 v[30:31], v[64:65], v[64:65], v[30:31]
	v_lshl_add_u64 v[14:15], v[2:3], 2, s[44:45]
	global_load_dwordx4 v[196:199], v[14:15], off
	global_load_dwordx4 v[200:203], v[14:15], off offset:32
	global_load_dwordx4 v[204:207], v[14:15], off offset:64
	global_load_dwordx4 v[208:211], v[14:15], off offset:96
	global_load_dwordx4 v[212:215], v[14:15], off offset:128
	global_load_dwordx4 v[216:219], v[14:15], off offset:160
	global_load_dwordx4 v[220:223], v[14:15], off offset:192
	global_load_dwordx4 v[224:227], v[14:15], off offset:224
	global_load_dwordx4 v[228:231], v[14:15], off offset:256
	global_load_dwordx4 v[232:235], v[14:15], off offset:288
	global_load_dwordx4 v[236:239], v[14:15], off offset:320
	global_load_dwordx4 v[240:243], v[14:15], off offset:352
	global_load_dwordx4 v[244:247], v[14:15], off offset:384
	global_load_dwordx4 v[248:251], v[14:15], off offset:416
	global_load_dwordx4 v[150:153], v[14:15], off offset:448
	global_load_dwordx4 v[154:157], v[14:15], off offset:480
; __device__ __forceinline__ float swap_add(float v) { auto rr = __builtin_amdgcn_permlane32_swap(__float_as_uint(v), __float_as_uint(v), false, false); return __uint_as_float(rr[0]) + __uint_as_float(rr[1]); }
; template <bool STORE> __device__ __forceinline__ void attn_unit(LAS unsigned char* lds, bf16_t* Q, const bf16_t* Kg, const bf16_t* VT, const float* subg, float lam, float outscale, int unit, const int wave_s) {
;     ...
;     if (STORE && map == 0) {
;         float ss = 0.f;
; #pragma unroll
;         for (int d = 0; d < 4; ++d)
; #pragma unroll
;             for (int r = 0; r < 16; ++r) { const float v = o[d][r] * inv - lam * xb[(d * 16 + r) * 64 + lane]; o[d][r] = v; ss += v * v; }
;         ss = swap_add(ss);
	v_pk_add_f32 v[30:31], v[30:31], v[72:73] op_sel_hi:[1,0]
	v_pk_mul_f32 v[72:73], s[14:15], v[140:141]
	v_pk_fma_f32 v[72:73], v[54:55], v[0:1], v[72:73] op_sel_hi:[1,0,1] neg_lo:[0,0,1] neg_hi:[0,0,1]
	v_pk_mul_f32 v[54:55], s[14:15], v[138:139]
	s_nop 0
	v_pk_fma_f32 v[78:79], v[52:53], v[0:1], v[54:55] op_sel_hi:[1,0,1] neg_lo:[0,0,1] neg_hi:[0,0,1]
	v_pk_mul_f32 v[52:53], s[14:15], v[102:103]
	s_nop 0
	v_pk_fma_f32 v[102:103], v[50:51], v[0:1], v[52:53] op_sel_hi:[1,0,1] neg_lo:[0,0,1] neg_hi:[0,0,1]
	v_pk_mul_f32 v[50:51], s[14:15], v[104:105]
	s_nop 0
	v_pk_fma_f32 v[104:105], v[48:49], v[0:1], v[50:51] op_sel_hi:[1,0,1] neg_lo:[0,0,1] neg_hi:[0,0,1]
	s_nop 0
	v_pk_fma_f32 v[30:31], v[104:105], v[104:105], v[30:31]
	v_mul_f32_e32 v48, v105, v105
	v_pk_add_f32 v[30:31], v[30:31], v[48:49] op_sel_hi:[1,0]
	v_mul_f32_e32 v48, v103, v103
	v_pk_fma_f32 v[30:31], v[102:103], v[102:103], v[30:31]
	s_nop 0
	v_pk_add_f32 v[30:31], v[30:31], v[48:49] op_sel_hi:[1,0]
	v_mul_f32_e32 v48, v79, v79
	v_pk_fma_f32 v[30:31], v[78:79], v[78:79], v[30:31]
	s_nop 0
	v_pk_add_f32 v[30:31], v[30:31], v[48:49] op_sel_hi:[1,0]
	v_mul_f32_e32 v48, v73, v73
	v_pk_fma_f32 v[30:31], v[72:73], v[72:73], v[30:31]
	s_nop 0
	v_pk_add_f32 v[30:31], v[30:31], v[48:49] op_sel_hi:[1,0]
	v_pk_mul_f32 v[48:49], s[14:15], v[124:125]
	s_nop 0
	v_pk_fma_f32 v[54:55], v[62:63], v[0:1], v[48:49] op_sel_hi:[1,0,1] neg_lo:[0,0,1] neg_hi:[0,0,1]
	v_pk_mul_f32 v[48:49], s[14:15], v[122:123]
	s_nop 0
	v_pk_fma_f32 v[60:61], v[60:61], v[0:1], v[48:49] op_sel_hi:[1,0,1] neg_lo:[0,0,1] neg_hi:[0,0,1]
	v_pk_mul_f32 v[48:49], s[14:15], v[120:121]
	s_nop 0
	v_pk_fma_f32 v[58:59], v[58:59], v[0:1], v[48:49] op_sel_hi:[1,0,1] neg_lo:[0,0,1] neg_hi:[0,0,1]
	v_pk_mul_f32 v[48:49], s[14:15], v[118:119]
	s_nop 0
	v_pk_fma_f32 v[62:63], v[56:57], v[0:1], v[48:49] op_sel_hi:[1,0,1] neg_lo:[0,0,1] neg_hi:[0,0,1]
	s_nop 0
	v_pk_fma_f32 v[30:31], v[62:63], v[62:63], v[30:31]
	v_mul_f32_e32 v48, v63, v63
	v_pk_add_f32 v[30:31], v[30:31], v[48:49] op_sel_hi:[1,0]
	v_mul_f32_e32 v48, v59, v59
	v_pk_fma_f32 v[30:31], v[58:59], v[58:59], v[30:31]
	s_nop 0
	v_pk_add_f32 v[30:31], v[30:31], v[48:49] op_sel_hi:[1,0]
	v_mul_f32_e32 v48, v61, v61
	v_pk_fma_f32 v[30:31], v[60:61], v[60:61], v[30:31]
	s_nop 0
	v_pk_add_f32 v[30:31], v[30:31], v[48:49] op_sel_hi:[1,0]
	v_mul_f32_e32 v48, v55, v55
	v_pk_fma_f32 v[30:31], v[54:55], v[54:55], v[30:31]
	s_nop 0
	v_pk_add_f32 v[30:31], v[30:31], v[48:49] op_sel_hi:[1,0]
	v_pk_mul_f32 v[48:49], s[14:15], v[116:117]
	s_nop 0
	v_pk_fma_f32 v[48:49], v[38:39], v[0:1], v[48:49] op_sel_hi:[1,0,1] neg_lo:[0,0,1] neg_hi:[0,0,1]
	v_pk_mul_f32 v[38:39], s[14:15], v[114:115]
	s_nop 0
	v_pk_fma_f32 v[50:51], v[36:37], v[0:1], v[38:39] op_sel_hi:[1,0,1] neg_lo:[0,0,1] neg_hi:[0,0,1]
	v_pk_mul_f32 v[36:37], s[14:15], v[112:113]
	s_nop 0
	v_pk_fma_f32 v[52:53], v[34:35], v[0:1], v[36:37] op_sel_hi:[1,0,1] neg_lo:[0,0,1] neg_hi:[0,0,1]
	v_pk_mul_f32 v[34:35], s[14:15], v[110:111]
	s_nop 0
	v_pk_fma_f32 v[56:57], v[32:33], v[0:1], v[34:35] op_sel_hi:[1,0,1] neg_lo:[0,0,1] neg_hi:[0,0,1]
	s_nop 0
	v_pk_fma_f32 v[30:31], v[56:57], v[56:57], v[30:31]
	v_mul_f32_e32 v32, v57, v57
	v_pk_add_f32 v[30:31], v[30:31], v[32:33] op_sel_hi:[1,0]
	v_mul_f32_e32 v32, v53, v53
	v_pk_fma_f32 v[30:31], v[52:53], v[52:53], v[30:31]
	s_nop 0
	v_pk_add_f32 v[30:31], v[30:31], v[32:33] op_sel_hi:[1,0]
	v_mul_f32_e32 v32, v51, v51
	v_pk_fma_f32 v[30:31], v[50:51], v[50:51], v[30:31]
	s_nop 0
	v_pk_add_f32 v[30:31], v[30:31], v[32:33] op_sel_hi:[1,0]
	v_mul_f32_e32 v32, v49, v49
	v_pk_fma_f32 v[30:31], v[48:49], v[48:49], v[30:31]
	s_nop 0
	v_pk_add_f32 v[30:31], v[30:31], v[32:33] op_sel_hi:[1,0]
	v_pk_mul_f32 v[32:33], s[14:15], v[108:109]
	s_nop 0
	v_pk_fma_f32 v[34:35], v[46:47], v[0:1], v[32:33] op_sel_hi:[1,0,1] neg_lo:[0,0,1] neg_hi:[0,0,1]
	v_pk_mul_f32 v[32:33], s[14:15], v[106:107]
	s_nop 0
	v_pk_fma_f32 v[38:39], v[44:45], v[0:1], v[32:33] op_sel_hi:[1,0,1] neg_lo:[0,0,1] neg_hi:[0,0,1]
	v_pk_mul_f32 v[32:33], s[14:15], v[100:101]
	s_nop 0
	v_pk_fma_f32 v[42:43], v[42:43], v[0:1], v[32:33] op_sel_hi:[1,0,1] neg_lo:[0,0,1] neg_hi:[0,0,1]
	v_pk_mul_f32 v[32:33], s[14:15], v[96:97]
	s_nop 0
	v_pk_fma_f32 v[40:41], v[40:41], v[0:1], v[32:33] op_sel_hi:[1,0,1] neg_lo:[0,0,1] neg_hi:[0,0,1]
	s_nop 0
	v_pk_fma_f32 v[30:31], v[40:41], v[40:41], v[30:31]
	v_mul_f32_e32 v32, v41, v41
	v_pk_add_f32 v[30:31], v[30:31], v[32:33] op_sel_hi:[1,0]
	v_mul_f32_e32 v32, v43, v43
	v_pk_fma_f32 v[30:31], v[42:43], v[42:43], v[30:31]
	s_nop 0
	v_pk_add_f32 v[30:31], v[30:31], v[32:33] op_sel_hi:[1,0]
	v_mul_f32_e32 v32, v39, v39
	v_pk_fma_f32 v[30:31], v[38:39], v[38:39], v[30:31]
	s_nop 0
	v_pk_add_f32 v[30:31], v[30:31], v[32:33] op_sel_hi:[1,0]
	v_mul_f32_e32 v32, v35, v35
	v_pk_fma_f32 v[30:31], v[34:35], v[34:35], v[30:31]
	s_nop 0
	v_pk_add_f32 v[44:45], v[30:31], v[32:33] op_sel_hi:[1,0]
	v_pk_mul_f32 v[30:31], s[14:15], v[94:95]
	s_nop 0
	v_pk_fma_f32 v[22:23], v[22:23], v[0:1], v[30:31] op_sel_hi:[1,0,1] neg_lo:[0,0,1] neg_hi:[0,0,1]
	v_pk_mul_f32 v[30:31], s[14:15], v[90:91]
	s_nop 0
	v_pk_fma_f32 v[30:31], v[20:21], v[0:1], v[30:31] op_sel_hi:[1,0,1] neg_lo:[0,0,1] neg_hi:[0,0,1]
	v_pk_mul_f32 v[20:21], s[14:15], v[88:89]
	s_nop 0
	v_pk_fma_f32 v[32:33], v[18:19], v[0:1], v[20:21] op_sel_hi:[1,0,1] neg_lo:[0,0,1] neg_hi:[0,0,1]
	v_pk_mul_f32 v[18:19], s[14:15], v[86:87]
	v_pk_mul_f32 v[20:21], s[14:15], v[80:81]
	v_pk_fma_f32 v[36:37], v[16:17], v[0:1], v[18:19] op_sel_hi:[1,0,1] neg_lo:[0,0,1] neg_hi:[0,0,1]
	v_pk_fma_f32 v[20:21], v[24:25], v[0:1], v[20:21] op_sel_hi:[1,0,1] neg_lo:[0,0,1] neg_hi:[0,0,1]
; __device__ __forceinline__ unsigned cvt_pk_bf16(float lo, float hi) { const f32x2 v = {lo, hi}; const bf16x2_t b = __builtin_convertvector(v, bf16x2_t); return __builtin_bit_cast(unsigned, b); }
; __device__ __forceinline__ int lane_op() { unsigned z = 0u; asm volatile("" : "+v"(z)); return (int)__builtin_amdgcn_mbcnt_hi(~0u, __builtin_amdgcn_mbcnt_lo(~0u, z)); }
; __device__ __forceinline__ float swap_add(float v) { auto rr = __builtin_amdgcn_permlane32_swap(__float_as_uint(v), __float_as_uint(v), false, false); return __uint_as_float(rr[0]) + __uint_as_float(rr[1]); }
; template <bool STORE> __device__ __forceinline__ void attn_unit(LAS unsigned char* lds, bf16_t* Q, const bf16_t* Kg, const bf16_t* VT, const float* subg, float lam, float outscale, int unit, const int wave_s) {
;     ...
;         ss = swap_add(ss);
;         const float rstd = outscale / sqrtf(ss * (1.f / 128.f) + EPS);
;         const int l2 = lane_op();
;         const int hi2 = l2 >> 5;
;         bf16_t* orow = Q + (size_t)(b * SEQ + qrow0 + (l2 & 31)) * DM + h * 128 + 8 * hi2;
; #pragma unroll
;         for (int d = 0; d < 4; ++d)
; #pragma unroll
;             for (int i = 0; i < 4; i += 2) {
;                 const f32x4 ga = *(const f32x4*)(subg + 32 * d + 8 * i + 4 * hi2), gb = *(const f32x4*)(subg + 32 * d + 8 * (i + 1) + 4 * hi2);
;                 u32x2 a, c; a.x = cvt_pk_bf16(o[d][4 * i] * rstd * ga[0], o[d][4 * i + 1] * rstd * ga[1]); a.y = cvt_pk_bf16(o[d][4 * i + 2] * rstd * ga[2], o[d][4 * i + 3] * rstd * ga[3]);
	v_pk_fma_f32 v[16:17], v[36:37], v[36:37], v[44:45]
	v_mul_f32_e32 v18, v37, v37
	v_pk_add_f32 v[16:17], v[16:17], v[18:19] op_sel_hi:[1,0]
	v_mul_f32_e32 v18, v33, v33
	v_pk_fma_f32 v[16:17], v[32:33], v[32:33], v[16:17]
	s_nop 0
	v_pk_add_f32 v[16:17], v[16:17], v[18:19] op_sel_hi:[1,0]
	v_mul_f32_e32 v18, v31, v31
	v_pk_fma_f32 v[16:17], v[30:31], v[30:31], v[16:17]
	s_nop 0
	v_pk_add_f32 v[16:17], v[16:17], v[18:19] op_sel_hi:[1,0]
	v_mul_f32_e32 v18, v23, v23
	v_pk_fma_f32 v[16:17], v[22:23], v[22:23], v[16:17]
	s_nop 0
	v_pk_add_f32 v[44:45], v[16:17], v[18:19] op_sel_hi:[1,0]
	v_pk_mul_f32 v[16:17], s[14:15], v[84:85]
	v_pk_mul_f32 v[18:19], s[14:15], v[82:83]
	v_pk_fma_f32 v[16:17], v[28:29], v[0:1], v[16:17] op_sel_hi:[1,0,1] neg_lo:[0,0,1] neg_hi:[0,0,1]
	v_pk_fma_f32 v[18:19], v[26:27], v[0:1], v[18:19] op_sel_hi:[1,0,1] neg_lo:[0,0,1] neg_hi:[0,0,1]
	v_pk_fma_f32 v[24:25], v[20:21], v[20:21], v[44:45]
	v_mul_f32_e32 v0, v21, v21
	v_pk_add_f32 v[24:25], v[24:25], v[0:1] op_sel_hi:[1,0]
	v_mul_f32_e32 v0, v19, v19
	v_pk_fma_f32 v[24:25], v[18:19], v[18:19], v[24:25]
	s_nop 0
	v_pk_add_f32 v[24:25], v[24:25], v[0:1] op_sel_hi:[1,0]
	v_mul_f32_e32 v0, v17, v17
	v_pk_fma_f32 v[24:25], v[16:17], v[16:17], v[24:25]
	s_nop 0
	v_pk_add_f32 v[24:25], v[24:25], v[0:1] op_sel_hi:[1,0]
	v_mul_f32_e32 v0, v13, v13
	v_pk_fma_f32 v[24:25], v[12:13], v[12:13], v[24:25]
	s_nop 0
	v_pk_add_f32 v[24:25], v[24:25], v[0:1] op_sel_hi:[1,0]
	s_nop 0
	v_mov_b32_e32 v0, v24
	s_nop 1
	v_permlane32_swap_b32_e32 v24, v0
	v_add_f32_e32 v0, v24, v0
	v_fmamk_f32 v0, v0, 0x3c000000, v193
	v_cmp_gt_f32_e32 vcc, s12, v0
	v_mul_f32_e32 v24, 0x4f800000, v0
	s_nop 0
	v_cndmask_b32_e32 v0, v0, v24, vcc
	v_sqrt_f32_e32 v24, v0
	s_nop 0
	v_add_u32_e32 v25, -1, v24
	v_fma_f32 v26, -v25, v24, v0
	v_cmp_ge_f32_e64 s[40:41], 0, v26
	v_add_u32_e32 v26, 1, v24
	s_nop 0
	v_cndmask_b32_e64 v25, v24, v25, s[40:41]
	v_fma_f32 v24, -v26, v24, v0
	v_cmp_lt_f32_e64 s[40:41], 0, v24
	s_nop 1
	v_cndmask_b32_e64 v24, v25, v26, s[40:41]
	v_mul_f32_e32 v25, 0x37800000, v24
	v_cndmask_b32_e32 v24, v24, v25, vcc
	v_cmp_class_f32_e32 vcc, v0, v194
	s_nop 1
	v_cndmask_b32_e32 v0, v24, v0, vcc
	v_div_scale_f32 v24, s[12:13], v0, v0, v192
	v_rcp_f32_e32 v25, v24
	s_nop 0
	v_fma_f32 v26, -v24, v25, 1.0
	v_fmac_f32_e32 v25, v26, v25
	v_div_scale_f32 v26, vcc, v192, v0, v192
	v_mul_f32_e32 v27, v26, v25
	v_fma_f32 v28, -v24, v27, v26
	v_fmac_f32_e32 v27, v28, v25
	v_fma_f32 v24, -v24, v27, v26
	v_div_fmas_f32 v24, v24, v25, v27
	v_div_fixup_f32 v0, v24, v0, v192
	v_pk_mul_f32 v[24:25], v[92:93], v[0:1] op_sel_hi:[1,0]
	s_waitcnt vmcnt(0)
; __device__ __forceinline__ unsigned cvt_pk_bf16(float lo, float hi) { const f32x2 v = {lo, hi}; const bf16x2_t b = __builtin_convertvector(v, bf16x2_t); return __builtin_bit_cast(unsigned, b); }
; __device__ __forceinline__ int lane_op() { unsigned z = 0u; asm volatile("" : "+v"(z)); return (int)__builtin_amdgcn_mbcnt_hi(~0u, __builtin_amdgcn_mbcnt_lo(~0u, z)); }
; template <bool STORE> __device__ __forceinline__ void attn_unit(LAS unsigned char* lds, bf16_t* Q, const bf16_t* Kg, const bf16_t* VT, const float* subg, float lam, float outscale, int unit, const int wave_s) {
;     ...
;         const int l2 = lane_op();
;         const int hi2 = l2 >> 5;
;         bf16_t* orow = Q + (size_t)(b * SEQ + qrow0 + (l2 & 31)) * DM + h * 128 + 8 * hi2;
; #pragma unroll
;         for (int d = 0; d < 4; ++d)
; #pragma unroll
;             for (int i = 0; i < 4; i += 2) {
;                 const f32x4 ga = *(const f32x4*)(subg + 32 * d + 8 * i + 4 * hi2), gb = *(const f32x4*)(subg + 32 * d + 8 * (i + 1) + 4 * hi2);
;                 u32x2 a, c; a.x = cvt_pk_bf16(o[d][4 * i] * rstd * ga[0], o[d][4 * i + 1] * rstd * ga[1]); a.y = cvt_pk_bf16(o[d][4 * i + 2] * rstd * ga[2], o[d][4 * i + 3] * rstd * ga[3]);
;                 c.x = cvt_pk_bf16(o[d][4 * i + 4] * rstd * gb[0], o[d][4 * i + 5] * rstd * gb[1]); c.y = cvt_pk_bf16(o[d][4 * i + 6] * rstd * gb[2], o[d][4 * i + 7] * rstd * gb[3]);
;                 { auto r = __builtin_amdgcn_permlane32_swap(a.x, c.x, false, false); a.x = r[0]; c.x = r[1]; }
;                 { auto r = __builtin_amdgcn_permlane32_swap(a.y, c.y, false, false); a.y = r[0]; c.y = r[1]; }
;                 u32x4 w; w.x = a.x; w.y = a.y; w.z = c.x; w.w = c.y;
;                 *(u32x4*)(orow + 32 * d + 8 * i) = w; }
	v_pk_mul_f32 v[6:7], v[196:197], v[24:25]
	v_pk_mul_f32 v[24:25], v[66:67], v[0:1] op_sel_hi:[1,0]
	v_cvt_pk_bf16_f32 v6, v6, v7
	v_pk_mul_f32 v[8:9], v[198:199], v[24:25]
	v_pk_mul_f32 v[24:25], v[98:99], v[0:1] op_sel_hi:[1,0]
	v_cvt_pk_bf16_f32 v7, v8, v9
	v_pk_mul_f32 v[8:9], v[68:69], v[0:1] op_sel_hi:[1,0]
	v_pk_mul_f32 v[2:3], v[200:201], v[8:9]
	s_nop 0
	v_cvt_pk_bf16_f32 v8, v2, v3
	v_pk_mul_f32 v[2:3], v[70:71], v[0:1] op_sel_hi:[1,0]
	s_nop 0
	v_permlane32_swap_b32_e32 v6, v8
	v_pk_mul_f32 v[2:3], v[202:203], v[2:3]
	s_nop 0
	v_cvt_pk_bf16_f32 v9, v2, v3
	s_nop 1
	v_permlane32_swap_b32_e32 v7, v9
	global_store_dwordx4 v[10:11], v[6:9], off
	s_nop 0
	v_pk_mul_f32 v[2:3], v[24:25], v[204:205]
	v_pk_mul_f32 v[24:25], v[74:75], v[0:1] op_sel_hi:[1,0]
	v_cvt_pk_bf16_f32 v2, v2, v3
	v_pk_mul_f32 v[4:5], v[24:25], v[206:207]
	v_pk_mul_f32 v[24:25], v[104:105], v[0:1] op_sel_hi:[1,0]
	v_cvt_pk_bf16_f32 v3, v4, v5
	v_pk_mul_f32 v[4:5], v[76:77], v[0:1] op_sel_hi:[1,0]
	v_pk_mul_f32 v[4:5], v[4:5], v[208:209]
	v_pk_mul_f32 v[6:7], v[64:65], v[0:1] op_sel_hi:[1,0]
	v_cvt_pk_bf16_f32 v4, v4, v5
	v_pk_mul_f32 v[6:7], v[6:7], v[210:211]
	s_nop 0
	v_permlane32_swap_b32_e32 v2, v4
	v_cvt_pk_bf16_f32 v5, v6, v7
	s_nop 1
	v_permlane32_swap_b32_e32 v3, v5
	global_store_dwordx4 v[10:11], v[2:5], off offset:32
	s_nop 0
	s_nop 0
	v_pk_mul_f32 v[2:3], v[24:25], v[212:213]
	v_pk_mul_f32 v[24:25], v[102:103], v[0:1] op_sel_hi:[1,0]
	v_cvt_pk_bf16_f32 v2, v2, v3
	v_pk_mul_f32 v[4:5], v[24:25], v[214:215]
	v_pk_mul_f32 v[24:25], v[62:63], v[0:1] op_sel_hi:[1,0]
	v_cvt_pk_bf16_f32 v3, v4, v5
	v_pk_mul_f32 v[4:5], v[78:79], v[0:1] op_sel_hi:[1,0]
	v_pk_mul_f32 v[4:5], v[4:5], v[216:217]
	v_pk_mul_f32 v[6:7], v[72:73], v[0:1] op_sel_hi:[1,0]
	v_cvt_pk_bf16_f32 v4, v4, v5
	v_pk_mul_f32 v[6:7], v[6:7], v[218:219]
	s_nop 0
	v_permlane32_swap_b32_e32 v2, v4
	v_cvt_pk_bf16_f32 v5, v6, v7
	s_nop 1
	v_permlane32_swap_b32_e32 v3, v5
	global_store_dwordx4 v[10:11], v[2:5], off offset:64
	s_nop 0
	s_nop 0
	v_pk_mul_f32 v[2:3], v[24:25], v[220:221]
	v_pk_mul_f32 v[24:25], v[58:59], v[0:1] op_sel_hi:[1,0]
	v_cvt_pk_bf16_f32 v2, v2, v3
	v_pk_mul_f32 v[4:5], v[24:25], v[222:223]
	v_pk_mul_f32 v[24:25], v[56:57], v[0:1] op_sel_hi:[1,0]
	v_cvt_pk_bf16_f32 v3, v4, v5
	v_pk_mul_f32 v[4:5], v[60:61], v[0:1] op_sel_hi:[1,0]
	v_pk_mul_f32 v[4:5], v[4:5], v[224:225]
	v_pk_mul_f32 v[6:7], v[54:55], v[0:1] op_sel_hi:[1,0]
	v_cvt_pk_bf16_f32 v4, v4, v5
	v_pk_mul_f32 v[6:7], v[6:7], v[226:227]
	s_nop 0
	v_permlane32_swap_b32_e32 v2, v4
	v_cvt_pk_bf16_f32 v5, v6, v7
	s_nop 1
	v_permlane32_swap_b32_e32 v3, v5
	global_store_dwordx4 v[10:11], v[2:5], off offset:96
	s_nop 0
	s_nop 0
	v_pk_mul_f32 v[2:3], v[24:25], v[228:229]
	v_pk_mul_f32 v[24:25], v[52:53], v[0:1] op_sel_hi:[1,0]
	v_cvt_pk_bf16_f32 v2, v2, v3
	v_pk_mul_f32 v[4:5], v[24:25], v[230:231]
	v_pk_mul_f32 v[24:25], v[40:41], v[0:1] op_sel_hi:[1,0]
	v_cvt_pk_bf16_f32 v3, v4, v5
	v_pk_mul_f32 v[4:5], v[50:51], v[0:1] op_sel_hi:[1,0]
	v_pk_mul_f32 v[4:5], v[4:5], v[232:233]
	v_pk_mul_f32 v[6:7], v[48:49], v[0:1] op_sel_hi:[1,0]
	v_cvt_pk_bf16_f32 v4, v4, v5
	v_pk_mul_f32 v[6:7], v[6:7], v[234:235]
	s_nop 0
	v_permlane32_swap_b32_e32 v2, v4
	v_cvt_pk_bf16_f32 v5, v6, v7
	s_nop 1
	v_permlane32_swap_b32_e32 v3, v5
	global_store_dwordx4 v[10:11], v[2:5], off offset:128
	s_nop 0
	s_nop 0
	v_pk_mul_f32 v[2:3], v[24:25], v[236:237]
	v_pk_mul_f32 v[24:25], v[42:43], v[0:1] op_sel_hi:[1,0]
	v_cvt_pk_bf16_f32 v2, v2, v3
	v_pk_mul_f32 v[4:5], v[24:25], v[238:239]
	v_pk_mul_f32 v[24:25], v[36:37], v[0:1] op_sel_hi:[1,0]
	v_cvt_pk_bf16_f32 v3, v4, v5
	v_pk_mul_f32 v[4:5], v[38:39], v[0:1] op_sel_hi:[1,0]
	v_pk_mul_f32 v[4:5], v[4:5], v[240:241]
	v_pk_mul_f32 v[6:7], v[34:35], v[0:1] op_sel_hi:[1,0]
	v_cvt_pk_bf16_f32 v4, v4, v5
	v_pk_mul_f32 v[6:7], v[6:7], v[242:243]
	s_nop 0
	v_permlane32_swap_b32_e32 v2, v4
	v_cvt_pk_bf16_f32 v5, v6, v7
	s_nop 1
	v_permlane32_swap_b32_e32 v3, v5
	global_store_dwordx4 v[10:11], v[2:5], off offset:160
	s_nop 0
	s_nop 0
	v_pk_mul_f32 v[2:3], v[24:25], v[244:245]
	v_pk_mul_f32 v[24:25], v[32:33], v[0:1] op_sel_hi:[1,0]
	v_cvt_pk_bf16_f32 v2, v2, v3
	v_pk_mul_f32 v[4:5], v[24:25], v[246:247]
	s_nop 0
	v_cvt_pk_bf16_f32 v3, v4, v5
	v_pk_mul_f32 v[4:5], v[30:31], v[0:1] op_sel_hi:[1,0]
	v_pk_mul_f32 v[4:5], v[4:5], v[248:249]
	v_pk_mul_f32 v[6:7], v[22:23], v[0:1] op_sel_hi:[1,0]
	v_cvt_pk_bf16_f32 v4, v4, v5
	v_pk_mul_f32 v[6:7], v[6:7], v[250:251]
	s_nop 0
	v_permlane32_swap_b32_e32 v2, v4
	v_cvt_pk_bf16_f32 v5, v6, v7
	s_nop 1
	v_permlane32_swap_b32_e32 v3, v5
	global_store_dwordx4 v[10:11], v[2:5], off offset:192
	s_nop 0
	v_pk_mul_f32 v[14:15], v[20:21], v[0:1] op_sel_hi:[1,0]
	v_pk_mul_f32 v[2:3], v[14:15], v[150:151]
	v_pk_mul_f32 v[14:15], v[18:19], v[0:1] op_sel_hi:[1,0]
	v_cvt_pk_bf16_f32 v2, v2, v3
	v_pk_mul_f32 v[4:5], v[14:15], v[152:153]
	s_nop 0
	v_cvt_pk_bf16_f32 v3, v4, v5
	v_pk_mul_f32 v[4:5], v[16:17], v[0:1] op_sel_hi:[1,0]
	v_pk_mul_f32 v[4:5], v[4:5], v[154:155]
	v_pk_mul_f32 v[6:7], v[12:13], v[0:1] op_sel_hi:[1,0]
	v_cvt_pk_bf16_f32 v4, v4, v5
	v_pk_mul_f32 v[6:7], v[6:7], v[156:157]
	s_nop 0
	v_permlane32_swap_b32_e32 v2, v4
	v_cvt_pk_bf16_f32 v5, v6, v7
	s_nop 1
	v_permlane32_swap_b32_e32 v3, v5
	global_store_dwordx4 v[10:11], v[2:5], off offset:224
	s_branch .LBB0_574

; __device__ __forceinline__ unsigned cvt_pk_bf16(float lo, float hi) { const f32x2 v = {lo, hi}; const bf16x2_t b = __builtin_convertvector(v, bf16x2_t); return __builtin_bit_cast(unsigned, b); }
; __device__ __forceinline__ int lane_id() { return (int)__builtin_amdgcn_mbcnt_hi(~0u, __builtin_amdgcn_mbcnt_lo(~0u, 0u)); }
; __device__ __forceinline__ void rms_rows4_to_bf16(const float* x0row, size_t rstride, const float* g, bf16_t* o0row, int lane) {
;     f32x4 v[4][4]; float s[4];
; #pragma unroll
;     for (int r = 0; r < 4; ++r) { const f32x4* xr = (const f32x4*)(x0row + r * rstride) + lane; s[r] = 0.f;
; #pragma unroll
;         for (int j = 0; j < 4; ++j) v[r][j] = xr[64 * j]; }
; #pragma unroll
;     for (int r = 0; r < 4; ++r)
; #pragma unroll
;         for (int j = 0; j < 4; ++j) s[r] += (v[r][j].x * v[r][j].x + v[r][j].y * v[r][j].y) + (v[r][j].z * v[r][j].z + v[r][j].w * v[r][j].w);
;     { int lid = lane_id(); asm volatile("" : "+v"(lid));
; #pragma unroll
;       for (int o = 1; o < 64; o <<= 1)
; #pragma unroll
;           for (int r = 0; r < 4; ++r) s[r] += __int_as_float(__builtin_amdgcn_ds_bpermute((lid ^ o) << 2, __float_as_int(s[r]))); }
;     const f32x4* gr = (const f32x4*)g + lane;
; #pragma unroll
;     for (int r = 0; r < 4; ++r) { const float rstd = __builtin_amdgcn_rsqf(s[r] * (1.f / DM) + EPS); u32x2* o8 = (u32x2*)(o0row + r * rstride) + lane;
; #pragma unroll
;         for (int j = 0; j < 4; ++j) { const f32x4 gg = gr[64 * j]; u32x2 w; w.x = cvt_pk_bf16(v[r][j].x * rstd * gg.x, v[r][j].y * rstd * gg.y); w.y = cvt_pk_bf16(v[r][j].z * rstd * gg.z, v[r][j].w * rstd * gg.w); o8[64 * j] = w; } }
; }
; __global__ void __launch_bounds__(NTHREADS, 2) fwd_megakernel(Args a_unused) {
;     ...
;             for (int m = gw; m < T; m += 4 * NGW) rms_rows4_to_bf16(x + (size_t)m * DM, (size_t)NGW * DM, g, XN + (size_t)m * DM, lane);
.LBB0_882:
	s_cmpk_gt_i32 s38, 0x3fff
	s_cbranch_scc1 .LBB0_885
	s_waitcnt lgkmcnt(0)
	s_load_dwordx4 s[12:15], s[0:1], 0x0
	s_ashr_i32 s7, s6, 31
	s_ashr_i32 s39, s38, 31
	s_lshl_b32 s0, s29, 5
	s_lshl_b64 s[8:9], s[6:7], 12
	s_lshl_b64 s[6:7], s[6:7], 11
	s_lshl_b64 s[10:11], s[38:39], 11
	s_add_u32 s4, s4, s10
	v_ashrrev_i32_e32 v3, 31, v2
	s_addc_u32 s5, s5, s11
	s_ashr_i32 s1, s0, 31
	v_lshl_add_u64 v[68:69], v[2:3], 3, s[4:5]
	s_lshl_b64 s[4:5], s[0:1], 11
	s_lshl_b64 s[10:11], s[38:39], 12
	s_waitcnt lgkmcnt(0)
	s_add_u32 s10, s12, s10
	v_lshlrev_b64 v[4:5], 4, v[2:3]
	s_addc_u32 s11, s13, s11
	v_lshl_add_u64 v[66:67], s[14:15], 0, v[4:5]
	global_load_dwordx4 v[150:153], v[66:67], off
	global_load_dwordx4 v[154:157], v[66:67], off offset:1024
	global_load_dwordx4 v[158:161], v[66:67], off offset:2048
	global_load_dwordx4 v[162:165], v[66:67], off offset:3072
	v_lshl_add_u64 v[70:71], s[10:11], 0, v[4:5]
	s_lshl_b64 s[10:11], s[0:1], 12
.LBB0_884:
	global_load_dwordx4 v[62:65], v[70:71], off
	global_load_dwordx4 v[58:61], v[70:71], off offset:1024
	global_load_dwordx4 v[50:53], v[70:71], off offset:3072
	global_load_dwordx4 v[54:57], v[70:71], off offset:2048
	v_lshl_add_u64 v[2:3], v[70:71], 0, s[8:9]
	global_load_dwordx4 v[46:49], v[2:3], off
	global_load_dwordx4 v[42:45], v[2:3], off offset:1024
	global_load_dwordx4 v[38:41], v[2:3], off offset:2048
	global_load_dwordx4 v[34:37], v[2:3], off offset:3072
	v_lshl_add_u64 v[2:3], v[2:3], 0, s[8:9]
	v_mov_b32_e32 v74, v195
	v_lshl_add_u64 v[14:15], v[2:3], 0, s[8:9]
	global_load_dwordx4 v[30:33], v[2:3], off
	global_load_dwordx4 v[26:29], v[2:3], off offset:1024
	global_load_dwordx4 v[22:25], v[2:3], off offset:2048
	global_load_dwordx4 v[10:13], v[2:3], off offset:3072
	s_add_i32 s38, s38, s0
	global_load_dwordx4 v[2:5], v[14:15], off
	v_lshl_add_u64 v[70:71], v[70:71], 0, s[10:11]
	s_cmpk_gt_i32 s38, 0x3fff
	s_waitcnt vmcnt(0)
	v_pk_mul_f32 v[6:7], v[64:65], v[64:65]
	v_pk_mul_f32 v[16:17], v[62:63], v[62:63]
	v_pk_mul_f32 v[8:9], v[60:61], v[60:61]
	v_pk_mul_f32 v[18:19], v[58:59], v[58:59]
	v_pk_mov_b32 v[20:21], v[16:17], v[6:7] op_sel:[1,0]
	v_mov_b32_e32 v17, v7
	v_mul_f32_e32 v0, v55, v55
	v_pk_mov_b32 v[72:73], v[18:19], v[8:9] op_sel:[1,0]
	v_mov_b32_e32 v19, v9
	v_pk_add_f32 v[16:17], v[20:21], v[16:17]
	v_pk_fma_f32 v[20:21], v[54:55], v[54:55], v[0:1] op_sel_hi:[1,1,0]
	v_mul_f32_e32 v0, v57, v57
	v_mul_f32_e32 v75, v52, v52
	v_mul_f32_e32 v76, v53, v53
	v_pk_add_f32 v[18:19], v[72:73], v[18:19]
	v_pk_fma_f32 v[72:73], v[56:57], v[56:57], v[0:1] op_sel_hi:[1,1,0]
	v_mov_b32_e32 v21, v75
	v_mov_b32_e32 v73, v76
	v_mul_f32_e32 v0, v50, v50
	v_pk_add_f32 v[72:73], v[20:21], v[72:73]
	v_mul_f32_e32 v20, v51, v51
	v_pk_add_f32 v[16:17], v[16:17], v[16:17] op_sel:[0,1] op_sel_hi:[1,0]
	v_pk_add_f32 v[18:19], v[18:19], v[18:19] op_sel:[0,1] op_sel_hi:[1,0]
	v_mov_b32_e32 v17, v0
	v_mov_b32_e32 v19, v20
	v_pk_add_f32 v[16:17], v[16:17], v[18:19]
	global_load_dwordx4 v[6:9], v[14:15], off offset:1024
	global_load_dwordx4 v[18:21], v[14:15], off offset:2048
	v_pk_add_f32 v[72:73], v[16:17], v[72:73]
	global_load_dwordx4 v[14:17], v[14:15], off offset:3072
	global_load_dwordx4 v[80:83], v[66:67], off
	v_lshlrev_b32_e32 v0, 2, v74
	v_xor_b32_e32 v74, 4, v0
	v_add_f32_e32 v72, v72, v73
	ds_bpermute_b32 v73, v74, v72
	v_xor_b32_e32 v75, 8, v0
	v_xor_b32_e32 v76, 16, v0
	v_xor_b32_e32 v77, 32, v0
	v_xor_b32_e32 v78, 64, v0
	s_waitcnt lgkmcnt(0)
	v_add_f32_e32 v72, v72, v73
	ds_bpermute_b32 v73, v75, v72
	v_xor_b32_e32 v79, 0x80, v0
	s_waitcnt lgkmcnt(0)
	v_add_f32_e32 v72, v72, v73
	ds_bpermute_b32 v73, v76, v72
	s_waitcnt lgkmcnt(0)
	v_add_f32_e32 v72, v72, v73
	ds_bpermute_b32 v73, v77, v72
	s_waitcnt lgkmcnt(0)
	v_add_f32_e32 v72, v72, v73
	ds_bpermute_b32 v73, v78, v72
	s_waitcnt lgkmcnt(0)
	v_add_f32_e32 v72, v72, v73
	ds_bpermute_b32 v0, v79, v72
	s_waitcnt lgkmcnt(0)
	v_add_f32_e32 v0, v72, v0
	v_fmamk_f32 v0, v0, 0x3a800000, v193
	v_rsq_f32_e32 v0, v0
	s_nop 0
	v_pk_mul_f32 v[72:73], v[62:63], v[0:1] op_sel_hi:[1,0]
	v_pk_mul_f32 v[62:63], v[64:65], v[0:1] op_sel_hi:[1,0]
	v_pk_mul_f32 v[50:51], v[50:51], v[0:1] op_sel_hi:[1,0]
	v_pk_mul_f32 v[52:53], v[52:53], v[0:1] op_sel_hi:[1,0]
	s_waitcnt vmcnt(0)
	s_waitcnt vmcnt(0)
	v_pk_mul_f32 v[64:65], v[80:81], v[72:73]
	v_pk_mul_f32 v[62:63], v[82:83], v[62:63]
	v_pk_mul_f32 v[72:73], v[58:59], v[0:1] op_sel_hi:[1,0]
	v_cvt_pk_bf16_f32 v58, v64, v65
	v_cvt_pk_bf16_f32 v59, v62, v63
	global_store_dwordx2 v[68:69], v[58:59], off
	v_pk_mul_f32 v[80:81], v[60:61], v[0:1] op_sel_hi:[1,0]
	v_pk_mul_f32 v[62:63], v[54:55], v[0:1] op_sel_hi:[1,0]
	v_pk_mul_f32 v[64:65], v[56:57], v[0:1] op_sel_hi:[1,0]
	v_mul_f32_e32 v0, v39, v39
	v_pk_mul_f32 v[58:59], v[72:73], v[154:155]
	v_pk_mul_f32 v[60:61], v[80:81], v[156:157]
	v_cvt_pk_bf16_f32 v54, v58, v59
	v_cvt_pk_bf16_f32 v55, v60, v61
	global_store_dwordx2 v[68:69], v[54:55], off offset:512
	v_pk_mul_f32 v[58:59], v[48:49], v[48:49]
	v_pk_mul_f32 v[60:61], v[46:47], v[46:47]
	v_pk_mul_f32 v[54:55], v[62:63], v[158:159]
	v_pk_mul_f32 v[56:57], v[64:65], v[160:161]
	v_cvt_pk_bf16_f32 v54, v54, v55
	v_cvt_pk_bf16_f32 v55, v56, v57
	global_store_dwordx2 v[68:69], v[54:55], off offset:1024
	v_pk_mul_f32 v[62:63], v[44:45], v[44:45]
	v_pk_mul_f32 v[50:51], v[50:51], v[162:163]
	v_pk_mul_f32 v[52:53], v[52:53], v[164:165]
	v_cvt_pk_bf16_f32 v50, v50, v51
	v_cvt_pk_bf16_f32 v51, v52, v53
	global_store_dwordx2 v[68:69], v[50:51], off offset:1536
	v_pk_mul_f32 v[54:55], v[42:43], v[42:43]
	v_pk_mov_b32 v[56:57], v[60:61], v[58:59] op_sel:[1,0]
	v_mov_b32_e32 v61, v59
	v_pk_mov_b32 v[58:59], v[54:55], v[62:63] op_sel:[1,0]
	v_mov_b32_e32 v55, v63
	v_pk_add_f32 v[54:55], v[58:59], v[54:55]
	v_mul_f32_e32 v58, v41, v41
	v_mul_f32_e32 v62, v36, v36
	v_mul_f32_e32 v63, v37, v37
	v_pk_add_f32 v[56:57], v[56:57], v[60:61]
	v_pk_fma_f32 v[60:61], v[38:39], v[38:39], v[0:1] op_sel_hi:[1,1,0]
	v_pk_fma_f32 v[58:59], v[40:41], v[40:41], v[58:59] op_sel_hi:[1,1,0]
	v_mov_b32_e32 v61, v62
	v_mov_b32_e32 v59, v63
	v_pk_add_f32 v[58:59], v[60:61], v[58:59]
	v_mul_f32_e32 v0, v34, v34
	v_mul_f32_e32 v60, v35, v35
	v_pk_add_f32 v[56:57], v[56:57], v[56:57] op_sel:[0,1] op_sel_hi:[1,0]
	v_pk_add_f32 v[54:55], v[54:55], v[54:55] op_sel:[0,1] op_sel_hi:[1,0]
	v_mov_b32_e32 v57, v0
	v_mov_b32_e32 v55, v60
	v_pk_add_f32 v[54:55], v[56:57], v[54:55]
	v_lshl_add_u64 v[62:63], v[68:69], 0, s[6:7]
	v_pk_add_f32 v[54:55], v[54:55], v[58:59]
	v_lshl_add_u64 v[68:69], v[68:69], 0, s[4:5]
	v_add_f32_e32 v0, v54, v55
	ds_bpermute_b32 v54, v74, v0
	v_mul_f32_e32 v55, v13, v13
	s_waitcnt lgkmcnt(0)
; __device__ __forceinline__ unsigned cvt_pk_bf16(float lo, float hi) { const f32x2 v = {lo, hi}; const bf16x2_t b = __builtin_convertvector(v, bf16x2_t); return __builtin_bit_cast(unsigned, b); }
; __device__ __forceinline__ int lane_id() { return (int)__builtin_amdgcn_mbcnt_hi(~0u, __builtin_amdgcn_mbcnt_lo(~0u, 0u)); }
; __device__ __forceinline__ void rms_rows4_to_bf16(const float* x0row, size_t rstride, const float* g, bf16_t* o0row, int lane) {
;     ...
;     { int lid = lane_id(); asm volatile("" : "+v"(lid));
; #pragma unroll
;       for (int o = 1; o < 64; o <<= 1)
; #pragma unroll
;           for (int r = 0; r < 4; ++r) s[r] += __int_as_float(__builtin_amdgcn_ds_bpermute((lid ^ o) << 2, __float_as_int(s[r]))); }
;     const f32x4* gr = (const f32x4*)g + lane;
; #pragma unroll
;     for (int r = 0; r < 4; ++r) { const float rstd = __builtin_amdgcn_rsqf(s[r] * (1.f / DM) + EPS); u32x2* o8 = (u32x2*)(o0row + r * rstride) + lane;
; #pragma unroll
;         for (int j = 0; j < 4; ++j) { const f32x4 gg = gr[64 * j]; u32x2 w; w.x = cvt_pk_bf16(v[r][j].x * rstd * gg.x, v[r][j].y * rstd * gg.y); w.y = cvt_pk_bf16(v[r][j].z * rstd * gg.z, v[r][j].w * rstd * gg.w); o8[64 * j] = w; } }
	v_add_f32_e32 v0, v0, v54
	ds_bpermute_b32 v54, v75, v0
	s_waitcnt lgkmcnt(0)
	v_add_f32_e32 v0, v0, v54
	ds_bpermute_b32 v54, v76, v0
	s_waitcnt lgkmcnt(0)
	v_add_f32_e32 v0, v0, v54
	ds_bpermute_b32 v54, v77, v0
	s_waitcnt lgkmcnt(0)
	v_add_f32_e32 v0, v0, v54
	ds_bpermute_b32 v54, v78, v0
	s_waitcnt lgkmcnt(0)
	v_add_f32_e32 v0, v0, v54
	ds_bpermute_b32 v54, v79, v0
	s_waitcnt lgkmcnt(0)
	v_add_f32_e32 v0, v0, v54
	v_fmamk_f32 v0, v0, 0x3a800000, v193
	v_rsq_f32_e32 v0, v0
	v_mul_f32_e32 v54, v12, v12
	v_pk_mul_f32 v[46:47], v[46:47], v[0:1] op_sel_hi:[1,0]
	v_pk_mul_f32 v[48:49], v[48:49], v[0:1] op_sel_hi:[1,0]
	v_pk_mul_f32 v[42:43], v[42:43], v[0:1] op_sel_hi:[1,0]
	v_pk_mul_f32 v[44:45], v[44:45], v[0:1] op_sel_hi:[1,0]
	v_pk_mul_f32 v[38:39], v[38:39], v[0:1] op_sel_hi:[1,0]
	v_pk_mul_f32 v[40:41], v[40:41], v[0:1] op_sel_hi:[1,0]
	v_pk_mul_f32 v[34:35], v[34:35], v[0:1] op_sel_hi:[1,0]
	v_pk_mul_f32 v[36:37], v[36:37], v[0:1] op_sel_hi:[1,0]
	v_mul_f32_e32 v0, v23, v23
	v_pk_mul_f32 v[46:47], v[46:47], v[150:151]
	v_pk_mul_f32 v[48:49], v[48:49], v[152:153]
	v_cvt_pk_bf16_f32 v46, v46, v47
	v_cvt_pk_bf16_f32 v47, v48, v49
	global_store_dwordx2 v[62:63], v[46:47], off
	v_pk_mul_f32 v[50:51], v[26:27], v[26:27]
	v_mul_f32_e32 v52, v10, v10
	v_mul_f32_e32 v53, v11, v11
	v_pk_mul_f32 v[42:43], v[42:43], v[154:155]
	v_pk_mul_f32 v[44:45], v[44:45], v[156:157]
	v_cvt_pk_bf16_f32 v42, v42, v43
	v_cvt_pk_bf16_f32 v43, v44, v45
	global_store_dwordx2 v[62:63], v[42:43], off offset:512
	v_pk_mul_f32 v[46:47], v[30:31], v[30:31]
	v_pk_mul_f32 v[48:49], v[28:29], v[28:29]
	v_pk_mul_f32 v[38:39], v[38:39], v[158:159]
	v_pk_mul_f32 v[40:41], v[40:41], v[160:161]
	v_cvt_pk_bf16_f32 v38, v38, v39
	v_cvt_pk_bf16_f32 v39, v40, v41
	global_store_dwordx2 v[62:63], v[38:39], off offset:1024
	v_pk_mul_f32 v[44:45], v[32:33], v[32:33]
	v_lshl_add_u64 v[42:43], v[62:63], 0, s[6:7]
	v_pk_mul_f32 v[34:35], v[34:35], v[162:163]
	v_pk_mul_f32 v[36:37], v[36:37], v[164:165]
	v_cvt_pk_bf16_f32 v34, v34, v35
	v_cvt_pk_bf16_f32 v35, v36, v37
	global_store_dwordx2 v[62:63], v[34:35], off offset:1536
	v_pk_mov_b32 v[40:41], v[46:47], v[44:45] op_sel:[1,0]
	v_mov_b32_e32 v47, v45
	v_pk_mov_b32 v[44:45], v[50:51], v[48:49] op_sel:[1,0]
	v_mov_b32_e32 v51, v49
	v_mul_f32_e32 v38, v25, v25
	v_pk_add_f32 v[40:41], v[40:41], v[46:47]
	v_pk_add_f32 v[44:45], v[44:45], v[50:51]
	v_pk_fma_f32 v[48:49], v[22:23], v[22:23], v[0:1] op_sel_hi:[1,1,0]
	v_pk_fma_f32 v[38:39], v[24:25], v[24:25], v[38:39] op_sel_hi:[1,1,0]
	v_pk_add_f32 v[40:41], v[40:41], v[40:41] op_sel:[0,1] op_sel_hi:[1,0]
	v_pk_add_f32 v[44:45], v[44:45], v[44:45] op_sel:[0,1] op_sel_hi:[1,0]
	v_mov_b32_e32 v49, v54
	v_mov_b32_e32 v39, v55
	v_mov_b32_e32 v41, v52
	v_mov_b32_e32 v45, v53
	v_pk_add_f32 v[38:39], v[48:49], v[38:39]
	v_pk_add_f32 v[40:41], v[40:41], v[44:45]
	s_nop 0
	v_pk_add_f32 v[38:39], v[40:41], v[38:39]
	s_nop 0
	v_add_f32_e32 v0, v38, v39
	ds_bpermute_b32 v38, v74, v0
	v_mul_f32_e32 v39, v17, v17
	s_waitcnt lgkmcnt(0)
	v_add_f32_e32 v0, v0, v38
	ds_bpermute_b32 v38, v75, v0
	s_waitcnt lgkmcnt(0)
	v_add_f32_e32 v0, v0, v38
	ds_bpermute_b32 v38, v76, v0
	s_waitcnt lgkmcnt(0)
	v_add_f32_e32 v0, v0, v38
	ds_bpermute_b32 v38, v77, v0
	s_waitcnt lgkmcnt(0)
	v_add_f32_e32 v0, v0, v38
	ds_bpermute_b32 v38, v78, v0
	s_waitcnt lgkmcnt(0)
	v_add_f32_e32 v0, v0, v38
	ds_bpermute_b32 v38, v79, v0
	s_waitcnt lgkmcnt(0)
; __device__ __forceinline__ unsigned cvt_pk_bf16(float lo, float hi) { const f32x2 v = {lo, hi}; const bf16x2_t b = __builtin_convertvector(v, bf16x2_t); return __builtin_bit_cast(unsigned, b); }
; __device__ __forceinline__ int lane_id() { return (int)__builtin_amdgcn_mbcnt_hi(~0u, __builtin_amdgcn_mbcnt_lo(~0u, 0u)); }
; __device__ __forceinline__ void rms_rows4_to_bf16(const float* x0row, size_t rstride, const float* g, bf16_t* o0row, int lane) {
;     ...
;     { int lid = lane_id(); asm volatile("" : "+v"(lid));
; #pragma unroll
;       for (int o = 1; o < 64; o <<= 1)
; #pragma unroll
;           for (int r = 0; r < 4; ++r) s[r] += __int_as_float(__builtin_amdgcn_ds_bpermute((lid ^ o) << 2, __float_as_int(s[r]))); }
;     const f32x4* gr = (const f32x4*)g + lane;
; #pragma unroll
;     for (int r = 0; r < 4; ++r) { const float rstd = __builtin_amdgcn_rsqf(s[r] * (1.f / DM) + EPS); u32x2* o8 = (u32x2*)(o0row + r * rstride) + lane;
; #pragma unroll
;         for (int j = 0; j < 4; ++j) { const f32x4 gg = gr[64 * j]; u32x2 w; w.x = cvt_pk_bf16(v[r][j].x * rstd * gg.x, v[r][j].y * rstd * gg.y); w.y = cvt_pk_bf16(v[r][j].z * rstd * gg.z, v[r][j].w * rstd * gg.w); o8[64 * j] = w; } }
; __global__ void __launch_bounds__(NTHREADS, 2) fwd_megakernel(Args a_unused) {
;     ...
;             for (int m = gw; m < T; m += 4 * NGW) rms_rows4_to_bf16(x + (size_t)m * DM, (size_t)NGW * DM, g, XN + (size_t)m * DM, lane);
	v_add_f32_e32 v0, v0, v38
	v_fmamk_f32 v0, v0, 0x3a800000, v193
	v_rsq_f32_e32 v0, v0
	v_mul_f32_e32 v38, v16, v16
	v_pk_mul_f32 v[30:31], v[30:31], v[0:1] op_sel_hi:[1,0]
	v_pk_mul_f32 v[32:33], v[32:33], v[0:1] op_sel_hi:[1,0]
	v_pk_mul_f32 v[26:27], v[26:27], v[0:1] op_sel_hi:[1,0]
	v_pk_mul_f32 v[28:29], v[28:29], v[0:1] op_sel_hi:[1,0]
	v_pk_mul_f32 v[22:23], v[22:23], v[0:1] op_sel_hi:[1,0]
	v_pk_mul_f32 v[24:25], v[24:25], v[0:1] op_sel_hi:[1,0]
	v_pk_mul_f32 v[10:11], v[10:11], v[0:1] op_sel_hi:[1,0]
	v_pk_mul_f32 v[12:13], v[12:13], v[0:1] op_sel_hi:[1,0]
	v_mul_f32_e32 v0, v19, v19
	v_pk_mul_f32 v[30:31], v[30:31], v[150:151]
	v_pk_mul_f32 v[32:33], v[32:33], v[152:153]
	v_cvt_pk_bf16_f32 v30, v30, v31
	v_cvt_pk_bf16_f32 v31, v32, v33
	global_store_dwordx2 v[42:43], v[30:31], off
	v_mul_f32_e32 v36, v14, v14
	v_mul_f32_e32 v37, v15, v15
	v_pk_mul_f32 v[26:27], v[26:27], v[154:155]
	v_pk_mul_f32 v[28:29], v[28:29], v[156:157]
	v_cvt_pk_bf16_f32 v26, v26, v27
	v_cvt_pk_bf16_f32 v27, v28, v29
	global_store_dwordx2 v[42:43], v[26:27], off offset:512
	v_pk_mul_f32 v[30:31], v[6:7], v[6:7]
	v_mul_f32_e32 v32, v21, v21
	v_pk_fma_f32 v[32:33], v[20:21], v[20:21], v[32:33] op_sel_hi:[1,1,0]
	v_pk_mul_f32 v[22:23], v[22:23], v[158:159]
	v_pk_mul_f32 v[24:25], v[24:25], v[160:161]
	v_cvt_pk_bf16_f32 v22, v22, v23
	v_cvt_pk_bf16_f32 v23, v24, v25
	global_store_dwordx2 v[42:43], v[22:23], off offset:1024
	v_pk_mul_f32 v[28:29], v[8:9], v[8:9]
	v_mov_b32_e32 v33, v39
	v_lshl_add_u64 v[26:27], v[42:43], 0, s[6:7]
	v_pk_mul_f32 v[10:11], v[10:11], v[162:163]
	v_pk_mul_f32 v[12:13], v[12:13], v[164:165]
	v_cvt_pk_bf16_f32 v10, v10, v11
	v_cvt_pk_bf16_f32 v11, v12, v13
	global_store_dwordx2 v[42:43], v[10:11], off offset:1536
	v_pk_mul_f32 v[22:23], v[4:5], v[4:5]
	v_pk_mul_f32 v[24:25], v[2:3], v[2:3]
	s_nop 0
	v_pk_mov_b32 v[34:35], v[24:25], v[22:23] op_sel:[1,0]
	v_mov_b32_e32 v25, v23
	v_pk_mov_b32 v[22:23], v[30:31], v[28:29] op_sel:[1,0]
	v_mov_b32_e32 v31, v29
	v_pk_add_f32 v[24:25], v[34:35], v[24:25]
	v_pk_add_f32 v[22:23], v[22:23], v[30:31]
	v_pk_fma_f32 v[28:29], v[18:19], v[18:19], v[0:1] op_sel_hi:[1,1,0]
	v_pk_add_f32 v[24:25], v[24:25], v[24:25] op_sel:[0,1] op_sel_hi:[1,0]
	v_pk_add_f32 v[22:23], v[22:23], v[22:23] op_sel:[0,1] op_sel_hi:[1,0]
	v_mov_b32_e32 v29, v38
	v_mov_b32_e32 v25, v36
	v_mov_b32_e32 v23, v37
	v_pk_add_f32 v[28:29], v[28:29], v[32:33]
	v_pk_add_f32 v[22:23], v[24:25], v[22:23]
	s_nop 0
	v_pk_add_f32 v[22:23], v[22:23], v[28:29]
	s_nop 0
	v_add_f32_e32 v0, v22, v23
	ds_bpermute_b32 v22, v74, v0
	s_waitcnt lgkmcnt(0)
	v_add_f32_e32 v0, v0, v22
	ds_bpermute_b32 v22, v75, v0
	s_waitcnt lgkmcnt(0)
	v_add_f32_e32 v0, v0, v22
	ds_bpermute_b32 v22, v76, v0
	s_waitcnt lgkmcnt(0)
	v_add_f32_e32 v0, v0, v22
	ds_bpermute_b32 v22, v77, v0
	s_waitcnt lgkmcnt(0)
	v_add_f32_e32 v0, v0, v22
	ds_bpermute_b32 v22, v78, v0
	s_waitcnt lgkmcnt(0)
	v_add_f32_e32 v0, v0, v22
	ds_bpermute_b32 v22, v79, v0
	s_waitcnt lgkmcnt(0)
	v_add_f32_e32 v0, v0, v22
	v_fmamk_f32 v0, v0, 0x3a800000, v193
	v_rsq_f32_e32 v0, v0
	s_nop 0
	v_pk_mul_f32 v[2:3], v[2:3], v[0:1] op_sel_hi:[1,0]
	v_pk_mul_f32 v[4:5], v[4:5], v[0:1] op_sel_hi:[1,0]
	v_pk_mul_f32 v[6:7], v[6:7], v[0:1] op_sel_hi:[1,0]
	v_pk_mul_f32 v[8:9], v[8:9], v[0:1] op_sel_hi:[1,0]
	v_pk_mul_f32 v[2:3], v[2:3], v[150:151]
	v_pk_mul_f32 v[4:5], v[4:5], v[152:153]
	v_cvt_pk_bf16_f32 v2, v2, v3
	v_cvt_pk_bf16_f32 v3, v4, v5
	global_store_dwordx2 v[26:27], v[2:3], off
	v_pk_mul_f32 v[2:3], v[6:7], v[154:155]
	v_pk_mul_f32 v[4:5], v[8:9], v[156:157]
	v_cvt_pk_bf16_f32 v2, v2, v3
	v_cvt_pk_bf16_f32 v3, v4, v5
	global_store_dwordx2 v[26:27], v[2:3], off offset:512
	v_pk_mul_f32 v[6:7], v[18:19], v[0:1] op_sel_hi:[1,0]
	v_pk_mul_f32 v[8:9], v[20:21], v[0:1] op_sel_hi:[1,0]
	v_pk_mul_f32 v[2:3], v[6:7], v[158:159]
	v_pk_mul_f32 v[4:5], v[8:9], v[160:161]
	v_cvt_pk_bf16_f32 v2, v2, v3
	v_cvt_pk_bf16_f32 v3, v4, v5
	global_store_dwordx2 v[26:27], v[2:3], off offset:1024
	v_pk_mul_f32 v[6:7], v[14:15], v[0:1] op_sel_hi:[1,0]
	v_pk_mul_f32 v[8:9], v[16:17], v[0:1] op_sel_hi:[1,0]
	v_pk_mul_f32 v[2:3], v[6:7], v[162:163]
	v_pk_mul_f32 v[4:5], v[8:9], v[164:165]
	v_cvt_pk_bf16_f32 v2, v2, v3
	v_cvt_pk_bf16_f32 v3, v4, v5
	global_store_dwordx2 v[26:27], v[2:3], off offset:1536
	s_cbranch_scc0 .LBB0_884
